# segment-2 state correction rewritten: z tile staged to per-wave LDS, broadcast ds_read_b64 + packed f32 FMA instead of v_readlane + v_fmac per element
# speedup vs baseline: 1.0211x; 1.0026x over previous
.LBB0_3057:
	s_lshr_b32 s2, s4, 7
	s_and_b32 s10, s4, 0x7f
	s_lshr_b32 s11, s2, 3
	s_mul_i32 s11, s11, 0x4100
	s_lshl_b32 s10, s10, 6
	s_add_i32 s11, s11, s10
	s_addk_i32 s11, 0x2100
	s_and_b32 s10, s2, 7
	s_lshl_b32 s10, s10, 7
	s_lshl_b32 s12, s11, 10
	s_add_u32 s12, s12, s10
	s_add_u32 s20, s14, s12
	s_addc_u32 s21, s15, 0
	s_lshl_b32 s12, s11, 11
	s_add_u32 s12, s12, s10
	s_add_u32 s28, s16, s12
	s_addc_u32 s29, s17, 0
	s_lshl_b32 s12, s2, 14
	s_mov_b32 s13, 0
	v_lshl_add_u64 v[122:123], v[66:67], 0, s[12:13]
	global_load_dwordx4 v[2:5], v[122:123], off offset:0
	global_load_dwordx4 v[6:9], v[122:123], off offset:16
	global_load_dwordx4 v[10:13], v[122:123], off offset:32
	global_load_dwordx4 v[14:17], v[122:123], off offset:48
	global_load_dwordx4 v[18:21], v[122:123], off offset:64
	global_load_dwordx4 v[22:25], v[122:123], off offset:80
	global_load_dwordx4 v[26:29], v[122:123], off offset:96
	global_load_dwordx4 v[30:33], v[122:123], off offset:112
	global_load_dwordx4 v[34:37], v[122:123], off offset:128
	global_load_dwordx4 v[38:41], v[122:123], off offset:144
	global_load_dwordx4 v[42:45], v[122:123], off offset:160
	global_load_dwordx4 v[46:49], v[122:123], off offset:176
	global_load_dwordx4 v[50:53], v[122:123], off offset:192
	global_load_dwordx4 v[54:57], v[122:123], off offset:208
	global_load_dwordx4 v[58:61], v[122:123], off offset:224
	global_load_dwordx4 v[62:65], v[122:123], off offset:240
	s_and_b32 s2, s4, 7
	s_lshl_b32 s2, s2, 14
	s_movk_i32 s12, 0x1000
	s_mov_b32 s13, 0
	v_lshrrev_b32_e32 v119, 1, v0
	v_and_b32_e32 v118, 31, v119
	v_lshrrev_b32_e32 v121, 5, v119
	v_lshlrev_b32_e32 v120, 2, v118
	v_lshl_add_u32 v120, v121, 10, v120
	v_lshlrev_b32_e32 v118, 3, v118
	v_lshl_add_u32 v118, v121, 8, v118
	v_add_u32_e32 v118, s2, v118
	v_mov_b32_e32 v121, 0
	s_nop 0
	v_lshl_add_u64 v[122:123], v[120:121], 0, s[20:21]
	global_load_dword v70, v[122:123], off offset:0
	global_load_dword v71, v[122:123], off offset:2048
	v_lshl_add_u64 v[122:123], v[122:123], 0, s[12:13]
	global_load_dword v72, v[122:123], off offset:0
	global_load_dword v73, v[122:123], off offset:2048
	v_lshl_add_u64 v[122:123], v[122:123], 0, s[12:13]
	global_load_dword v74, v[122:123], off offset:0
	global_load_dword v75, v[122:123], off offset:2048
	v_lshl_add_u64 v[122:123], v[122:123], 0, s[12:13]
	global_load_dword v76, v[122:123], off offset:0
	global_load_dword v77, v[122:123], off offset:2048
	v_lshl_add_u64 v[122:123], v[122:123], 0, s[12:13]
	global_load_dword v78, v[122:123], off offset:0
	global_load_dword v79, v[122:123], off offset:2048
	v_lshl_add_u64 v[122:123], v[122:123], 0, s[12:13]
	global_load_dword v80, v[122:123], off offset:0
	global_load_dword v81, v[122:123], off offset:2048
	v_lshl_add_u64 v[122:123], v[122:123], 0, s[12:13]
	global_load_dword v82, v[122:123], off offset:0
	global_load_dword v83, v[122:123], off offset:2048
	v_lshl_add_u64 v[122:123], v[122:123], 0, s[12:13]
	global_load_dword v84, v[122:123], off offset:0
	global_load_dword v85, v[122:123], off offset:2048
	v_lshl_add_u64 v[122:123], v[122:123], 0, s[12:13]
	global_load_dword v86, v[122:123], off offset:0
	global_load_dword v87, v[122:123], off offset:2048
	v_lshl_add_u64 v[122:123], v[122:123], 0, s[12:13]
	global_load_dword v88, v[122:123], off offset:0
	global_load_dword v89, v[122:123], off offset:2048
	v_lshl_add_u64 v[122:123], v[122:123], 0, s[12:13]
	global_load_dword v90, v[122:123], off offset:0
	global_load_dword v91, v[122:123], off offset:2048
	v_lshl_add_u64 v[122:123], v[122:123], 0, s[12:13]
	global_load_dword v92, v[122:123], off offset:0
	global_load_dword v93, v[122:123], off offset:2048
	v_lshl_add_u64 v[122:123], v[122:123], 0, s[12:13]
	global_load_dword v94, v[122:123], off offset:0
	global_load_dword v95, v[122:123], off offset:2048
	v_lshl_add_u64 v[122:123], v[122:123], 0, s[12:13]
	global_load_dword v96, v[122:123], off offset:0
	global_load_dword v97, v[122:123], off offset:2048
	v_lshl_add_u64 v[122:123], v[122:123], 0, s[12:13]
	global_load_dword v98, v[122:123], off offset:0
	global_load_dword v99, v[122:123], off offset:2048
	v_lshl_add_u64 v[122:123], v[122:123], 0, s[12:13]
	global_load_dword v100, v[122:123], off offset:0
	global_load_dword v101, v[122:123], off offset:2048
	v_mov_b32_e32 v120, v0
	v_lshl_add_u64 v[120:121], v[120:121], 0, s[28:29]
	v_mov_b64_e32 v[122:123], v[120:121]
	s_waitcnt vmcnt(0)
	v_lshlrev_b32_e32 v102, 16, v70
	v_and_b32_e32 v103, 0xffff0000, v70
	ds_write_b64 v118, v[102:103] offset:0
	v_lshlrev_b32_e32 v104, 16, v71
	v_and_b32_e32 v105, 0xffff0000, v71
	ds_write_b64 v118, v[104:105] offset:512
	v_lshlrev_b32_e32 v106, 16, v72
	v_and_b32_e32 v107, 0xffff0000, v72
	ds_write_b64 v118, v[106:107] offset:1024
	v_lshlrev_b32_e32 v108, 16, v73
	v_and_b32_e32 v109, 0xffff0000, v73
	ds_write_b64 v118, v[108:109] offset:1536
	v_lshlrev_b32_e32 v110, 16, v74
	v_and_b32_e32 v111, 0xffff0000, v74
	ds_write_b64 v118, v[110:111] offset:2048
	v_lshlrev_b32_e32 v112, 16, v75
	v_and_b32_e32 v113, 0xffff0000, v75
	ds_write_b64 v118, v[112:113] offset:2560
	v_lshlrev_b32_e32 v114, 16, v76
	v_and_b32_e32 v115, 0xffff0000, v76
	ds_write_b64 v118, v[114:115] offset:3072
	v_lshlrev_b32_e32 v116, 16, v77
	v_and_b32_e32 v117, 0xffff0000, v77
	ds_write_b64 v118, v[116:117] offset:3584
	v_lshlrev_b32_e32 v102, 16, v78
	v_and_b32_e32 v103, 0xffff0000, v78
	ds_write_b64 v118, v[102:103] offset:4096
	v_lshlrev_b32_e32 v104, 16, v79
	v_and_b32_e32 v105, 0xffff0000, v79
	ds_write_b64 v118, v[104:105] offset:4608
	v_lshlrev_b32_e32 v106, 16, v80
	v_and_b32_e32 v107, 0xffff0000, v80
	ds_write_b64 v118, v[106:107] offset:5120
	v_lshlrev_b32_e32 v108, 16, v81
	v_and_b32_e32 v109, 0xffff0000, v81
	ds_write_b64 v118, v[108:109] offset:5632
	v_lshlrev_b32_e32 v110, 16, v82
	v_and_b32_e32 v111, 0xffff0000, v82
	ds_write_b64 v118, v[110:111] offset:6144
	v_lshlrev_b32_e32 v112, 16, v83
	v_and_b32_e32 v113, 0xffff0000, v83
	ds_write_b64 v118, v[112:113] offset:6656
	v_lshlrev_b32_e32 v114, 16, v84
	v_and_b32_e32 v115, 0xffff0000, v84
	ds_write_b64 v118, v[114:115] offset:7168
	v_lshlrev_b32_e32 v116, 16, v85
	v_and_b32_e32 v117, 0xffff0000, v85
	ds_write_b64 v118, v[116:117] offset:7680
	v_lshlrev_b32_e32 v102, 16, v86
	v_and_b32_e32 v103, 0xffff0000, v86
	ds_write_b64 v118, v[102:103] offset:8192
	v_lshlrev_b32_e32 v104, 16, v87
	v_and_b32_e32 v105, 0xffff0000, v87
	ds_write_b64 v118, v[104:105] offset:8704
	v_lshlrev_b32_e32 v106, 16, v88
	v_and_b32_e32 v107, 0xffff0000, v88
	ds_write_b64 v118, v[106:107] offset:9216
	v_lshlrev_b32_e32 v108, 16, v89
	v_and_b32_e32 v109, 0xffff0000, v89
	ds_write_b64 v118, v[108:109] offset:9728
	v_lshlrev_b32_e32 v110, 16, v90
	v_and_b32_e32 v111, 0xffff0000, v90
	ds_write_b64 v118, v[110:111] offset:10240
	v_lshlrev_b32_e32 v112, 16, v91
	v_and_b32_e32 v113, 0xffff0000, v91
	ds_write_b64 v118, v[112:113] offset:10752
	v_lshlrev_b32_e32 v114, 16, v92
	v_and_b32_e32 v115, 0xffff0000, v92
	ds_write_b64 v118, v[114:115] offset:11264
	v_lshlrev_b32_e32 v116, 16, v93
	v_and_b32_e32 v117, 0xffff0000, v93
	ds_write_b64 v118, v[116:117] offset:11776
	v_lshlrev_b32_e32 v102, 16, v94
	v_and_b32_e32 v103, 0xffff0000, v94
	ds_write_b64 v118, v[102:103] offset:12288
	v_lshlrev_b32_e32 v104, 16, v95
	v_and_b32_e32 v105, 0xffff0000, v95
	ds_write_b64 v118, v[104:105] offset:12800
	v_lshlrev_b32_e32 v106, 16, v96
	v_and_b32_e32 v107, 0xffff0000, v96
	ds_write_b64 v118, v[106:107] offset:13312
	v_lshlrev_b32_e32 v108, 16, v97
	v_and_b32_e32 v109, 0xffff0000, v97
	ds_write_b64 v118, v[108:109] offset:13824
	v_lshlrev_b32_e32 v110, 16, v98
	v_and_b32_e32 v111, 0xffff0000, v98
	ds_write_b64 v118, v[110:111] offset:14336
	v_lshlrev_b32_e32 v112, 16, v99
	v_and_b32_e32 v113, 0xffff0000, v99
	ds_write_b64 v118, v[112:113] offset:14848
	v_lshlrev_b32_e32 v114, 16, v100
	v_and_b32_e32 v115, 0xffff0000, v100
	ds_write_b64 v118, v[114:115] offset:15360
	v_lshlrev_b32_e32 v116, 16, v101
	v_and_b32_e32 v117, 0xffff0000, v101
	ds_write_b64 v118, v[116:117] offset:15872
	v_mov_b32_e32 v118, s2
	s_mov_b32 s19, 0
	s_waitcnt lgkmcnt(0)
.Lcorr_pass:
	global_load_ushort v180, v[120:121], off offset:0
	global_load_ushort v181, v[120:121], off offset:2048
	v_lshl_add_u64 v[120:121], v[120:121], 0, s[12:13]
	global_load_ushort v182, v[120:121], off offset:0
	global_load_ushort v183, v[120:121], off offset:2048
	v_lshl_add_u64 v[120:121], v[120:121], 0, s[12:13]
	global_load_ushort v184, v[120:121], off offset:0
	global_load_ushort v185, v[120:121], off offset:2048
	v_lshl_add_u64 v[120:121], v[120:121], 0, s[12:13]
	global_load_ushort v186, v[120:121], off offset:0
	global_load_ushort v187, v[120:121], off offset:2048
	v_lshl_add_u64 v[120:121], v[120:121], 0, s[12:13]
	ds_read_b64 v[86:87], v118 offset:0
	ds_read_b64 v[88:89], v118 offset:256
	ds_read_b64 v[90:91], v118 offset:512
	ds_read_b64 v[92:93], v118 offset:768
	ds_read_b64 v[94:95], v118 offset:1024
	ds_read_b64 v[96:97], v118 offset:1280
	ds_read_b64 v[98:99], v118 offset:1536
	ds_read_b64 v[100:101], v118 offset:1792
	s_waitcnt lgkmcnt(0)
	ds_read_b64 v[102:103], v118 offset:8
	ds_read_b64 v[104:105], v118 offset:264
	ds_read_b64 v[106:107], v118 offset:520
	ds_read_b64 v[108:109], v118 offset:776
	ds_read_b64 v[110:111], v118 offset:1032
	ds_read_b64 v[112:113], v118 offset:1288
	ds_read_b64 v[114:115], v118 offset:1544
	ds_read_b64 v[116:117], v118 offset:1800
	v_pk_mul_f32 v[70:71], v[86:87], v[2:3]
	v_pk_mul_f32 v[72:73], v[88:89], v[2:3]
	v_pk_mul_f32 v[74:75], v[90:91], v[2:3]
	v_pk_mul_f32 v[76:77], v[92:93], v[2:3]
	v_pk_mul_f32 v[78:79], v[94:95], v[2:3]
	v_pk_mul_f32 v[80:81], v[96:97], v[2:3]
	v_pk_mul_f32 v[82:83], v[98:99], v[2:3]
	v_pk_mul_f32 v[84:85], v[100:101], v[2:3]
	s_waitcnt lgkmcnt(0)
	ds_read_b64 v[86:87], v118 offset:16
	ds_read_b64 v[88:89], v118 offset:272
	ds_read_b64 v[90:91], v118 offset:528
	ds_read_b64 v[92:93], v118 offset:784
	ds_read_b64 v[94:95], v118 offset:1040
	ds_read_b64 v[96:97], v118 offset:1296
	ds_read_b64 v[98:99], v118 offset:1552
	ds_read_b64 v[100:101], v118 offset:1808
	v_pk_fma_f32 v[70:71], v[102:103], v[4:5], v[70:71]
	v_pk_fma_f32 v[72:73], v[104:105], v[4:5], v[72:73]
	v_pk_fma_f32 v[74:75], v[106:107], v[4:5], v[74:75]
	v_pk_fma_f32 v[76:77], v[108:109], v[4:5], v[76:77]
	v_pk_fma_f32 v[78:79], v[110:111], v[4:5], v[78:79]
	v_pk_fma_f32 v[80:81], v[112:113], v[4:5], v[80:81]
	v_pk_fma_f32 v[82:83], v[114:115], v[4:5], v[82:83]
	v_pk_fma_f32 v[84:85], v[116:117], v[4:5], v[84:85]
	s_waitcnt lgkmcnt(0)
	ds_read_b64 v[102:103], v118 offset:24
	ds_read_b64 v[104:105], v118 offset:280
	ds_read_b64 v[106:107], v118 offset:536
	ds_read_b64 v[108:109], v118 offset:792
	ds_read_b64 v[110:111], v118 offset:1048
	ds_read_b64 v[112:113], v118 offset:1304
	ds_read_b64 v[114:115], v118 offset:1560
	ds_read_b64 v[116:117], v118 offset:1816
	v_pk_fma_f32 v[70:71], v[86:87], v[6:7], v[70:71]
	v_pk_fma_f32 v[72:73], v[88:89], v[6:7], v[72:73]
	v_pk_fma_f32 v[74:75], v[90:91], v[6:7], v[74:75]
	v_pk_fma_f32 v[76:77], v[92:93], v[6:7], v[76:77]
	v_pk_fma_f32 v[78:79], v[94:95], v[6:7], v[78:79]
	v_pk_fma_f32 v[80:81], v[96:97], v[6:7], v[80:81]
	v_pk_fma_f32 v[82:83], v[98:99], v[6:7], v[82:83]
	v_pk_fma_f32 v[84:85], v[100:101], v[6:7], v[84:85]
	s_waitcnt lgkmcnt(0)
	ds_read_b64 v[86:87], v118 offset:32
	ds_read_b64 v[88:89], v118 offset:288
	ds_read_b64 v[90:91], v118 offset:544
	ds_read_b64 v[92:93], v118 offset:800
	ds_read_b64 v[94:95], v118 offset:1056
	ds_read_b64 v[96:97], v118 offset:1312
	ds_read_b64 v[98:99], v118 offset:1568
	ds_read_b64 v[100:101], v118 offset:1824
	v_pk_fma_f32 v[70:71], v[102:103], v[8:9], v[70:71]
	v_pk_fma_f32 v[72:73], v[104:105], v[8:9], v[72:73]
	v_pk_fma_f32 v[74:75], v[106:107], v[8:9], v[74:75]
	v_pk_fma_f32 v[76:77], v[108:109], v[8:9], v[76:77]
	v_pk_fma_f32 v[78:79], v[110:111], v[8:9], v[78:79]
	v_pk_fma_f32 v[80:81], v[112:113], v[8:9], v[80:81]
	v_pk_fma_f32 v[82:83], v[114:115], v[8:9], v[82:83]
	v_pk_fma_f32 v[84:85], v[116:117], v[8:9], v[84:85]
	s_waitcnt lgkmcnt(0)
	ds_read_b64 v[102:103], v118 offset:40
	ds_read_b64 v[104:105], v118 offset:296
	ds_read_b64 v[106:107], v118 offset:552
	ds_read_b64 v[108:109], v118 offset:808
	ds_read_b64 v[110:111], v118 offset:1064
	ds_read_b64 v[112:113], v118 offset:1320
	ds_read_b64 v[114:115], v118 offset:1576
	ds_read_b64 v[116:117], v118 offset:1832
	v_pk_fma_f32 v[70:71], v[86:87], v[10:11], v[70:71]
	v_pk_fma_f32 v[72:73], v[88:89], v[10:11], v[72:73]
	v_pk_fma_f32 v[74:75], v[90:91], v[10:11], v[74:75]
	v_pk_fma_f32 v[76:77], v[92:93], v[10:11], v[76:77]
	v_pk_fma_f32 v[78:79], v[94:95], v[10:11], v[78:79]
	v_pk_fma_f32 v[80:81], v[96:97], v[10:11], v[80:81]
	v_pk_fma_f32 v[82:83], v[98:99], v[10:11], v[82:83]
	v_pk_fma_f32 v[84:85], v[100:101], v[10:11], v[84:85]
	s_waitcnt lgkmcnt(0)
	ds_read_b64 v[86:87], v118 offset:48
	ds_read_b64 v[88:89], v118 offset:304
	ds_read_b64 v[90:91], v118 offset:560
	ds_read_b64 v[92:93], v118 offset:816
	ds_read_b64 v[94:95], v118 offset:1072
	ds_read_b64 v[96:97], v118 offset:1328
	ds_read_b64 v[98:99], v118 offset:1584
	ds_read_b64 v[100:101], v118 offset:1840
	v_pk_fma_f32 v[70:71], v[102:103], v[12:13], v[70:71]
	v_pk_fma_f32 v[72:73], v[104:105], v[12:13], v[72:73]
	v_pk_fma_f32 v[74:75], v[106:107], v[12:13], v[74:75]
	v_pk_fma_f32 v[76:77], v[108:109], v[12:13], v[76:77]
	v_pk_fma_f32 v[78:79], v[110:111], v[12:13], v[78:79]
	v_pk_fma_f32 v[80:81], v[112:113], v[12:13], v[80:81]
	v_pk_fma_f32 v[82:83], v[114:115], v[12:13], v[82:83]
	v_pk_fma_f32 v[84:85], v[116:117], v[12:13], v[84:85]
	s_waitcnt lgkmcnt(0)
	ds_read_b64 v[102:103], v118 offset:56
	ds_read_b64 v[104:105], v118 offset:312
	ds_read_b64 v[106:107], v118 offset:568
	ds_read_b64 v[108:109], v118 offset:824
	ds_read_b64 v[110:111], v118 offset:1080
	ds_read_b64 v[112:113], v118 offset:1336
	ds_read_b64 v[114:115], v118 offset:1592
	ds_read_b64 v[116:117], v118 offset:1848
	v_pk_fma_f32 v[70:71], v[86:87], v[14:15], v[70:71]
	v_pk_fma_f32 v[72:73], v[88:89], v[14:15], v[72:73]
	v_pk_fma_f32 v[74:75], v[90:91], v[14:15], v[74:75]
	v_pk_fma_f32 v[76:77], v[92:93], v[14:15], v[76:77]
	v_pk_fma_f32 v[78:79], v[94:95], v[14:15], v[78:79]
	v_pk_fma_f32 v[80:81], v[96:97], v[14:15], v[80:81]
	v_pk_fma_f32 v[82:83], v[98:99], v[14:15], v[82:83]
	v_pk_fma_f32 v[84:85], v[100:101], v[14:15], v[84:85]
	s_waitcnt lgkmcnt(0)
	ds_read_b64 v[86:87], v118 offset:64
	ds_read_b64 v[88:89], v118 offset:320
	ds_read_b64 v[90:91], v118 offset:576
	ds_read_b64 v[92:93], v118 offset:832
	ds_read_b64 v[94:95], v118 offset:1088
	ds_read_b64 v[96:97], v118 offset:1344
	ds_read_b64 v[98:99], v118 offset:1600
	ds_read_b64 v[100:101], v118 offset:1856
	v_pk_fma_f32 v[70:71], v[102:103], v[16:17], v[70:71]
	v_pk_fma_f32 v[72:73], v[104:105], v[16:17], v[72:73]
	v_pk_fma_f32 v[74:75], v[106:107], v[16:17], v[74:75]
	v_pk_fma_f32 v[76:77], v[108:109], v[16:17], v[76:77]
	v_pk_fma_f32 v[78:79], v[110:111], v[16:17], v[78:79]
	v_pk_fma_f32 v[80:81], v[112:113], v[16:17], v[80:81]
	v_pk_fma_f32 v[82:83], v[114:115], v[16:17], v[82:83]
	v_pk_fma_f32 v[84:85], v[116:117], v[16:17], v[84:85]
	s_waitcnt lgkmcnt(0)
	ds_read_b64 v[102:103], v118 offset:72
	ds_read_b64 v[104:105], v118 offset:328
	ds_read_b64 v[106:107], v118 offset:584
	ds_read_b64 v[108:109], v118 offset:840
	ds_read_b64 v[110:111], v118 offset:1096
	ds_read_b64 v[112:113], v118 offset:1352
	ds_read_b64 v[114:115], v118 offset:1608
	ds_read_b64 v[116:117], v118 offset:1864
	v_pk_fma_f32 v[70:71], v[86:87], v[18:19], v[70:71]
	v_pk_fma_f32 v[72:73], v[88:89], v[18:19], v[72:73]
	v_pk_fma_f32 v[74:75], v[90:91], v[18:19], v[74:75]
	v_pk_fma_f32 v[76:77], v[92:93], v[18:19], v[76:77]
	v_pk_fma_f32 v[78:79], v[94:95], v[18:19], v[78:79]
	v_pk_fma_f32 v[80:81], v[96:97], v[18:19], v[80:81]
	v_pk_fma_f32 v[82:83], v[98:99], v[18:19], v[82:83]
	v_pk_fma_f32 v[84:85], v[100:101], v[18:19], v[84:85]
	s_waitcnt lgkmcnt(0)
	ds_read_b64 v[86:87], v118 offset:80
	ds_read_b64 v[88:89], v118 offset:336
	ds_read_b64 v[90:91], v118 offset:592
	ds_read_b64 v[92:93], v118 offset:848
	ds_read_b64 v[94:95], v118 offset:1104
	ds_read_b64 v[96:97], v118 offset:1360
	ds_read_b64 v[98:99], v118 offset:1616
	ds_read_b64 v[100:101], v118 offset:1872
	v_pk_fma_f32 v[70:71], v[102:103], v[20:21], v[70:71]
	v_pk_fma_f32 v[72:73], v[104:105], v[20:21], v[72:73]
	v_pk_fma_f32 v[74:75], v[106:107], v[20:21], v[74:75]
	v_pk_fma_f32 v[76:77], v[108:109], v[20:21], v[76:77]
	v_pk_fma_f32 v[78:79], v[110:111], v[20:21], v[78:79]
	v_pk_fma_f32 v[80:81], v[112:113], v[20:21], v[80:81]
	v_pk_fma_f32 v[82:83], v[114:115], v[20:21], v[82:83]
	v_pk_fma_f32 v[84:85], v[116:117], v[20:21], v[84:85]
	s_waitcnt lgkmcnt(0)
	ds_read_b64 v[102:103], v118 offset:88
	ds_read_b64 v[104:105], v118 offset:344
	ds_read_b64 v[106:107], v118 offset:600
	ds_read_b64 v[108:109], v118 offset:856
	ds_read_b64 v[110:111], v118 offset:1112
	ds_read_b64 v[112:113], v118 offset:1368
	ds_read_b64 v[114:115], v118 offset:1624
	ds_read_b64 v[116:117], v118 offset:1880
	v_pk_fma_f32 v[70:71], v[86:87], v[22:23], v[70:71]
	v_pk_fma_f32 v[72:73], v[88:89], v[22:23], v[72:73]
	v_pk_fma_f32 v[74:75], v[90:91], v[22:23], v[74:75]
	v_pk_fma_f32 v[76:77], v[92:93], v[22:23], v[76:77]
	v_pk_fma_f32 v[78:79], v[94:95], v[22:23], v[78:79]
	v_pk_fma_f32 v[80:81], v[96:97], v[22:23], v[80:81]
	v_pk_fma_f32 v[82:83], v[98:99], v[22:23], v[82:83]
	v_pk_fma_f32 v[84:85], v[100:101], v[22:23], v[84:85]
	s_waitcnt lgkmcnt(0)
	ds_read_b64 v[86:87], v118 offset:96
	ds_read_b64 v[88:89], v118 offset:352
	ds_read_b64 v[90:91], v118 offset:608
	ds_read_b64 v[92:93], v118 offset:864
	ds_read_b64 v[94:95], v118 offset:1120
	ds_read_b64 v[96:97], v118 offset:1376
	ds_read_b64 v[98:99], v118 offset:1632
	ds_read_b64 v[100:101], v118 offset:1888
	v_pk_fma_f32 v[70:71], v[102:103], v[24:25], v[70:71]
	v_pk_fma_f32 v[72:73], v[104:105], v[24:25], v[72:73]
	v_pk_fma_f32 v[74:75], v[106:107], v[24:25], v[74:75]
	v_pk_fma_f32 v[76:77], v[108:109], v[24:25], v[76:77]
	v_pk_fma_f32 v[78:79], v[110:111], v[24:25], v[78:79]
	v_pk_fma_f32 v[80:81], v[112:113], v[24:25], v[80:81]
	v_pk_fma_f32 v[82:83], v[114:115], v[24:25], v[82:83]
	v_pk_fma_f32 v[84:85], v[116:117], v[24:25], v[84:85]
	s_waitcnt lgkmcnt(0)
	ds_read_b64 v[102:103], v118 offset:104
	ds_read_b64 v[104:105], v118 offset:360
	ds_read_b64 v[106:107], v118 offset:616
	ds_read_b64 v[108:109], v118 offset:872
	ds_read_b64 v[110:111], v118 offset:1128
	ds_read_b64 v[112:113], v118 offset:1384
	ds_read_b64 v[114:115], v118 offset:1640
	ds_read_b64 v[116:117], v118 offset:1896
	v_pk_fma_f32 v[70:71], v[86:87], v[26:27], v[70:71]
	v_pk_fma_f32 v[72:73], v[88:89], v[26:27], v[72:73]
	v_pk_fma_f32 v[74:75], v[90:91], v[26:27], v[74:75]
	v_pk_fma_f32 v[76:77], v[92:93], v[26:27], v[76:77]
	v_pk_fma_f32 v[78:79], v[94:95], v[26:27], v[78:79]
	v_pk_fma_f32 v[80:81], v[96:97], v[26:27], v[80:81]
	v_pk_fma_f32 v[82:83], v[98:99], v[26:27], v[82:83]
	v_pk_fma_f32 v[84:85], v[100:101], v[26:27], v[84:85]
	s_waitcnt lgkmcnt(0)
	ds_read_b64 v[86:87], v118 offset:112
	ds_read_b64 v[88:89], v118 offset:368
	ds_read_b64 v[90:91], v118 offset:624
	ds_read_b64 v[92:93], v118 offset:880
	ds_read_b64 v[94:95], v118 offset:1136
	ds_read_b64 v[96:97], v118 offset:1392
	ds_read_b64 v[98:99], v118 offset:1648
	ds_read_b64 v[100:101], v118 offset:1904
	v_pk_fma_f32 v[70:71], v[102:103], v[28:29], v[70:71]
	v_pk_fma_f32 v[72:73], v[104:105], v[28:29], v[72:73]
	v_pk_fma_f32 v[74:75], v[106:107], v[28:29], v[74:75]
	v_pk_fma_f32 v[76:77], v[108:109], v[28:29], v[76:77]
	v_pk_fma_f32 v[78:79], v[110:111], v[28:29], v[78:79]
	v_pk_fma_f32 v[80:81], v[112:113], v[28:29], v[80:81]
	v_pk_fma_f32 v[82:83], v[114:115], v[28:29], v[82:83]
	v_pk_fma_f32 v[84:85], v[116:117], v[28:29], v[84:85]
	s_waitcnt lgkmcnt(0)
	ds_read_b64 v[102:103], v118 offset:120
	ds_read_b64 v[104:105], v118 offset:376
	ds_read_b64 v[106:107], v118 offset:632
	ds_read_b64 v[108:109], v118 offset:888
	ds_read_b64 v[110:111], v118 offset:1144
	ds_read_b64 v[112:113], v118 offset:1400
	ds_read_b64 v[114:115], v118 offset:1656
	ds_read_b64 v[116:117], v118 offset:1912
	v_pk_fma_f32 v[70:71], v[86:87], v[30:31], v[70:71]
	v_pk_fma_f32 v[72:73], v[88:89], v[30:31], v[72:73]
	v_pk_fma_f32 v[74:75], v[90:91], v[30:31], v[74:75]
	v_pk_fma_f32 v[76:77], v[92:93], v[30:31], v[76:77]
	v_pk_fma_f32 v[78:79], v[94:95], v[30:31], v[78:79]
	v_pk_fma_f32 v[80:81], v[96:97], v[30:31], v[80:81]
	v_pk_fma_f32 v[82:83], v[98:99], v[30:31], v[82:83]
	v_pk_fma_f32 v[84:85], v[100:101], v[30:31], v[84:85]
	s_waitcnt lgkmcnt(0)
	ds_read_b64 v[86:87], v118 offset:128
	ds_read_b64 v[88:89], v118 offset:384
	ds_read_b64 v[90:91], v118 offset:640
	ds_read_b64 v[92:93], v118 offset:896
	ds_read_b64 v[94:95], v118 offset:1152
	ds_read_b64 v[96:97], v118 offset:1408
	ds_read_b64 v[98:99], v118 offset:1664
	ds_read_b64 v[100:101], v118 offset:1920
	v_pk_fma_f32 v[70:71], v[102:103], v[32:33], v[70:71]
	v_pk_fma_f32 v[72:73], v[104:105], v[32:33], v[72:73]
	v_pk_fma_f32 v[74:75], v[106:107], v[32:33], v[74:75]
	v_pk_fma_f32 v[76:77], v[108:109], v[32:33], v[76:77]
	v_pk_fma_f32 v[78:79], v[110:111], v[32:33], v[78:79]
	v_pk_fma_f32 v[80:81], v[112:113], v[32:33], v[80:81]
	v_pk_fma_f32 v[82:83], v[114:115], v[32:33], v[82:83]
	v_pk_fma_f32 v[84:85], v[116:117], v[32:33], v[84:85]
	s_waitcnt lgkmcnt(0)
	ds_read_b64 v[102:103], v118 offset:136
	ds_read_b64 v[104:105], v118 offset:392
	ds_read_b64 v[106:107], v118 offset:648
	ds_read_b64 v[108:109], v118 offset:904
	ds_read_b64 v[110:111], v118 offset:1160
	ds_read_b64 v[112:113], v118 offset:1416
	ds_read_b64 v[114:115], v118 offset:1672
	ds_read_b64 v[116:117], v118 offset:1928
	v_pk_fma_f32 v[70:71], v[86:87], v[34:35], v[70:71]
	v_pk_fma_f32 v[72:73], v[88:89], v[34:35], v[72:73]
	v_pk_fma_f32 v[74:75], v[90:91], v[34:35], v[74:75]
	v_pk_fma_f32 v[76:77], v[92:93], v[34:35], v[76:77]
	v_pk_fma_f32 v[78:79], v[94:95], v[34:35], v[78:79]
	v_pk_fma_f32 v[80:81], v[96:97], v[34:35], v[80:81]
	v_pk_fma_f32 v[82:83], v[98:99], v[34:35], v[82:83]
	v_pk_fma_f32 v[84:85], v[100:101], v[34:35], v[84:85]
	s_waitcnt lgkmcnt(0)
	ds_read_b64 v[86:87], v118 offset:144
	ds_read_b64 v[88:89], v118 offset:400
	ds_read_b64 v[90:91], v118 offset:656
	ds_read_b64 v[92:93], v118 offset:912
	ds_read_b64 v[94:95], v118 offset:1168
	ds_read_b64 v[96:97], v118 offset:1424
	ds_read_b64 v[98:99], v118 offset:1680
	ds_read_b64 v[100:101], v118 offset:1936
	v_pk_fma_f32 v[70:71], v[102:103], v[36:37], v[70:71]
	v_pk_fma_f32 v[72:73], v[104:105], v[36:37], v[72:73]
	v_pk_fma_f32 v[74:75], v[106:107], v[36:37], v[74:75]
	v_pk_fma_f32 v[76:77], v[108:109], v[36:37], v[76:77]
	v_pk_fma_f32 v[78:79], v[110:111], v[36:37], v[78:79]
	v_pk_fma_f32 v[80:81], v[112:113], v[36:37], v[80:81]
	v_pk_fma_f32 v[82:83], v[114:115], v[36:37], v[82:83]
	v_pk_fma_f32 v[84:85], v[116:117], v[36:37], v[84:85]
	s_waitcnt lgkmcnt(0)
	ds_read_b64 v[102:103], v118 offset:152
	ds_read_b64 v[104:105], v118 offset:408
	ds_read_b64 v[106:107], v118 offset:664
	ds_read_b64 v[108:109], v118 offset:920
	ds_read_b64 v[110:111], v118 offset:1176
	ds_read_b64 v[112:113], v118 offset:1432
	ds_read_b64 v[114:115], v118 offset:1688
	ds_read_b64 v[116:117], v118 offset:1944
	v_pk_fma_f32 v[70:71], v[86:87], v[38:39], v[70:71]
	v_pk_fma_f32 v[72:73], v[88:89], v[38:39], v[72:73]
	v_pk_fma_f32 v[74:75], v[90:91], v[38:39], v[74:75]
	v_pk_fma_f32 v[76:77], v[92:93], v[38:39], v[76:77]
	v_pk_fma_f32 v[78:79], v[94:95], v[38:39], v[78:79]
	v_pk_fma_f32 v[80:81], v[96:97], v[38:39], v[80:81]
	v_pk_fma_f32 v[82:83], v[98:99], v[38:39], v[82:83]
	v_pk_fma_f32 v[84:85], v[100:101], v[38:39], v[84:85]
	s_waitcnt lgkmcnt(0)
	ds_read_b64 v[86:87], v118 offset:160
	ds_read_b64 v[88:89], v118 offset:416
	ds_read_b64 v[90:91], v118 offset:672
	ds_read_b64 v[92:93], v118 offset:928
	ds_read_b64 v[94:95], v118 offset:1184
	ds_read_b64 v[96:97], v118 offset:1440
	ds_read_b64 v[98:99], v118 offset:1696
	ds_read_b64 v[100:101], v118 offset:1952
	v_pk_fma_f32 v[70:71], v[102:103], v[40:41], v[70:71]
	v_pk_fma_f32 v[72:73], v[104:105], v[40:41], v[72:73]
	v_pk_fma_f32 v[74:75], v[106:107], v[40:41], v[74:75]
	v_pk_fma_f32 v[76:77], v[108:109], v[40:41], v[76:77]
	v_pk_fma_f32 v[78:79], v[110:111], v[40:41], v[78:79]
	v_pk_fma_f32 v[80:81], v[112:113], v[40:41], v[80:81]
	v_pk_fma_f32 v[82:83], v[114:115], v[40:41], v[82:83]
	v_pk_fma_f32 v[84:85], v[116:117], v[40:41], v[84:85]
	s_waitcnt lgkmcnt(0)
	ds_read_b64 v[102:103], v118 offset:168
	ds_read_b64 v[104:105], v118 offset:424
	ds_read_b64 v[106:107], v118 offset:680
	ds_read_b64 v[108:109], v118 offset:936
	ds_read_b64 v[110:111], v118 offset:1192
	ds_read_b64 v[112:113], v118 offset:1448
	ds_read_b64 v[114:115], v118 offset:1704
	ds_read_b64 v[116:117], v118 offset:1960
	v_pk_fma_f32 v[70:71], v[86:87], v[42:43], v[70:71]
	v_pk_fma_f32 v[72:73], v[88:89], v[42:43], v[72:73]
	v_pk_fma_f32 v[74:75], v[90:91], v[42:43], v[74:75]
	v_pk_fma_f32 v[76:77], v[92:93], v[42:43], v[76:77]
	v_pk_fma_f32 v[78:79], v[94:95], v[42:43], v[78:79]
	v_pk_fma_f32 v[80:81], v[96:97], v[42:43], v[80:81]
	v_pk_fma_f32 v[82:83], v[98:99], v[42:43], v[82:83]
	v_pk_fma_f32 v[84:85], v[100:101], v[42:43], v[84:85]
	s_waitcnt lgkmcnt(0)
	ds_read_b64 v[86:87], v118 offset:176
	ds_read_b64 v[88:89], v118 offset:432
	ds_read_b64 v[90:91], v118 offset:688
	ds_read_b64 v[92:93], v118 offset:944
	ds_read_b64 v[94:95], v118 offset:1200
	ds_read_b64 v[96:97], v118 offset:1456
	ds_read_b64 v[98:99], v118 offset:1712
	ds_read_b64 v[100:101], v118 offset:1968
	v_pk_fma_f32 v[70:71], v[102:103], v[44:45], v[70:71]
	v_pk_fma_f32 v[72:73], v[104:105], v[44:45], v[72:73]
	v_pk_fma_f32 v[74:75], v[106:107], v[44:45], v[74:75]
	v_pk_fma_f32 v[76:77], v[108:109], v[44:45], v[76:77]
	v_pk_fma_f32 v[78:79], v[110:111], v[44:45], v[78:79]
	v_pk_fma_f32 v[80:81], v[112:113], v[44:45], v[80:81]
	v_pk_fma_f32 v[82:83], v[114:115], v[44:45], v[82:83]
	v_pk_fma_f32 v[84:85], v[116:117], v[44:45], v[84:85]
	s_waitcnt lgkmcnt(0)
	ds_read_b64 v[102:103], v118 offset:184
	ds_read_b64 v[104:105], v118 offset:440
	ds_read_b64 v[106:107], v118 offset:696
	ds_read_b64 v[108:109], v118 offset:952
	ds_read_b64 v[110:111], v118 offset:1208
	ds_read_b64 v[112:113], v118 offset:1464
	ds_read_b64 v[114:115], v118 offset:1720
	ds_read_b64 v[116:117], v118 offset:1976
	v_pk_fma_f32 v[70:71], v[86:87], v[46:47], v[70:71]
	v_pk_fma_f32 v[72:73], v[88:89], v[46:47], v[72:73]
	v_pk_fma_f32 v[74:75], v[90:91], v[46:47], v[74:75]
	v_pk_fma_f32 v[76:77], v[92:93], v[46:47], v[76:77]
	v_pk_fma_f32 v[78:79], v[94:95], v[46:47], v[78:79]
	v_pk_fma_f32 v[80:81], v[96:97], v[46:47], v[80:81]
	v_pk_fma_f32 v[82:83], v[98:99], v[46:47], v[82:83]
	v_pk_fma_f32 v[84:85], v[100:101], v[46:47], v[84:85]
	s_waitcnt lgkmcnt(0)
	ds_read_b64 v[86:87], v118 offset:192
	ds_read_b64 v[88:89], v118 offset:448
	ds_read_b64 v[90:91], v118 offset:704
	ds_read_b64 v[92:93], v118 offset:960
	ds_read_b64 v[94:95], v118 offset:1216
	ds_read_b64 v[96:97], v118 offset:1472
	ds_read_b64 v[98:99], v118 offset:1728
	ds_read_b64 v[100:101], v118 offset:1984
	v_pk_fma_f32 v[70:71], v[102:103], v[48:49], v[70:71]
	v_pk_fma_f32 v[72:73], v[104:105], v[48:49], v[72:73]
	v_pk_fma_f32 v[74:75], v[106:107], v[48:49], v[74:75]
	v_pk_fma_f32 v[76:77], v[108:109], v[48:49], v[76:77]
	v_pk_fma_f32 v[78:79], v[110:111], v[48:49], v[78:79]
	v_pk_fma_f32 v[80:81], v[112:113], v[48:49], v[80:81]
	v_pk_fma_f32 v[82:83], v[114:115], v[48:49], v[82:83]
	v_pk_fma_f32 v[84:85], v[116:117], v[48:49], v[84:85]
	s_waitcnt lgkmcnt(0)
	ds_read_b64 v[102:103], v118 offset:200
	ds_read_b64 v[104:105], v118 offset:456
	ds_read_b64 v[106:107], v118 offset:712
	ds_read_b64 v[108:109], v118 offset:968
	ds_read_b64 v[110:111], v118 offset:1224
	ds_read_b64 v[112:113], v118 offset:1480
	ds_read_b64 v[114:115], v118 offset:1736
	ds_read_b64 v[116:117], v118 offset:1992
	v_pk_fma_f32 v[70:71], v[86:87], v[50:51], v[70:71]
	v_pk_fma_f32 v[72:73], v[88:89], v[50:51], v[72:73]
	v_pk_fma_f32 v[74:75], v[90:91], v[50:51], v[74:75]
	v_pk_fma_f32 v[76:77], v[92:93], v[50:51], v[76:77]
	v_pk_fma_f32 v[78:79], v[94:95], v[50:51], v[78:79]
	v_pk_fma_f32 v[80:81], v[96:97], v[50:51], v[80:81]
	v_pk_fma_f32 v[82:83], v[98:99], v[50:51], v[82:83]
	v_pk_fma_f32 v[84:85], v[100:101], v[50:51], v[84:85]
	s_waitcnt lgkmcnt(0)
	ds_read_b64 v[86:87], v118 offset:208
	ds_read_b64 v[88:89], v118 offset:464
	ds_read_b64 v[90:91], v118 offset:720
	ds_read_b64 v[92:93], v118 offset:976
	ds_read_b64 v[94:95], v118 offset:1232
	ds_read_b64 v[96:97], v118 offset:1488
	ds_read_b64 v[98:99], v118 offset:1744
	ds_read_b64 v[100:101], v118 offset:2000
	v_pk_fma_f32 v[70:71], v[102:103], v[52:53], v[70:71]
	v_pk_fma_f32 v[72:73], v[104:105], v[52:53], v[72:73]
	v_pk_fma_f32 v[74:75], v[106:107], v[52:53], v[74:75]
	v_pk_fma_f32 v[76:77], v[108:109], v[52:53], v[76:77]
	v_pk_fma_f32 v[78:79], v[110:111], v[52:53], v[78:79]
	v_pk_fma_f32 v[80:81], v[112:113], v[52:53], v[80:81]
	v_pk_fma_f32 v[82:83], v[114:115], v[52:53], v[82:83]
	v_pk_fma_f32 v[84:85], v[116:117], v[52:53], v[84:85]
	s_waitcnt lgkmcnt(0)
	ds_read_b64 v[102:103], v118 offset:216
	ds_read_b64 v[104:105], v118 offset:472
	ds_read_b64 v[106:107], v118 offset:728
	ds_read_b64 v[108:109], v118 offset:984
	ds_read_b64 v[110:111], v118 offset:1240
	ds_read_b64 v[112:113], v118 offset:1496
	ds_read_b64 v[114:115], v118 offset:1752
	ds_read_b64 v[116:117], v118 offset:2008
	v_pk_fma_f32 v[70:71], v[86:87], v[54:55], v[70:71]
	v_pk_fma_f32 v[72:73], v[88:89], v[54:55], v[72:73]
	v_pk_fma_f32 v[74:75], v[90:91], v[54:55], v[74:75]
	v_pk_fma_f32 v[76:77], v[92:93], v[54:55], v[76:77]
	v_pk_fma_f32 v[78:79], v[94:95], v[54:55], v[78:79]
	v_pk_fma_f32 v[80:81], v[96:97], v[54:55], v[80:81]
	v_pk_fma_f32 v[82:83], v[98:99], v[54:55], v[82:83]
	v_pk_fma_f32 v[84:85], v[100:101], v[54:55], v[84:85]
	s_waitcnt lgkmcnt(0)
	ds_read_b64 v[86:87], v118 offset:224
	ds_read_b64 v[88:89], v118 offset:480
	ds_read_b64 v[90:91], v118 offset:736
	ds_read_b64 v[92:93], v118 offset:992
	ds_read_b64 v[94:95], v118 offset:1248
	ds_read_b64 v[96:97], v118 offset:1504
	ds_read_b64 v[98:99], v118 offset:1760
	ds_read_b64 v[100:101], v118 offset:2016
	v_pk_fma_f32 v[70:71], v[102:103], v[56:57], v[70:71]
	v_pk_fma_f32 v[72:73], v[104:105], v[56:57], v[72:73]
	v_pk_fma_f32 v[74:75], v[106:107], v[56:57], v[74:75]
	v_pk_fma_f32 v[76:77], v[108:109], v[56:57], v[76:77]
	v_pk_fma_f32 v[78:79], v[110:111], v[56:57], v[78:79]
	v_pk_fma_f32 v[80:81], v[112:113], v[56:57], v[80:81]
	v_pk_fma_f32 v[82:83], v[114:115], v[56:57], v[82:83]
	v_pk_fma_f32 v[84:85], v[116:117], v[56:57], v[84:85]
	s_waitcnt lgkmcnt(0)
	ds_read_b64 v[102:103], v118 offset:232
	ds_read_b64 v[104:105], v118 offset:488
	ds_read_b64 v[106:107], v118 offset:744
	ds_read_b64 v[108:109], v118 offset:1000
	ds_read_b64 v[110:111], v118 offset:1256
	ds_read_b64 v[112:113], v118 offset:1512
	ds_read_b64 v[114:115], v118 offset:1768
	ds_read_b64 v[116:117], v118 offset:2024
	v_pk_fma_f32 v[70:71], v[86:87], v[58:59], v[70:71]
	v_pk_fma_f32 v[72:73], v[88:89], v[58:59], v[72:73]
	v_pk_fma_f32 v[74:75], v[90:91], v[58:59], v[74:75]
	v_pk_fma_f32 v[76:77], v[92:93], v[58:59], v[76:77]
	v_pk_fma_f32 v[78:79], v[94:95], v[58:59], v[78:79]
	v_pk_fma_f32 v[80:81], v[96:97], v[58:59], v[80:81]
	v_pk_fma_f32 v[82:83], v[98:99], v[58:59], v[82:83]
	v_pk_fma_f32 v[84:85], v[100:101], v[58:59], v[84:85]
	s_waitcnt lgkmcnt(0)
	ds_read_b64 v[86:87], v118 offset:240
	ds_read_b64 v[88:89], v118 offset:496
	ds_read_b64 v[90:91], v118 offset:752
	ds_read_b64 v[92:93], v118 offset:1008
	ds_read_b64 v[94:95], v118 offset:1264
	ds_read_b64 v[96:97], v118 offset:1520
	ds_read_b64 v[98:99], v118 offset:1776
	ds_read_b64 v[100:101], v118 offset:2032
	v_pk_fma_f32 v[70:71], v[102:103], v[60:61], v[70:71]
	v_pk_fma_f32 v[72:73], v[104:105], v[60:61], v[72:73]
	v_pk_fma_f32 v[74:75], v[106:107], v[60:61], v[74:75]
	v_pk_fma_f32 v[76:77], v[108:109], v[60:61], v[76:77]
	v_pk_fma_f32 v[78:79], v[110:111], v[60:61], v[78:79]
	v_pk_fma_f32 v[80:81], v[112:113], v[60:61], v[80:81]
	v_pk_fma_f32 v[82:83], v[114:115], v[60:61], v[82:83]
	v_pk_fma_f32 v[84:85], v[116:117], v[60:61], v[84:85]
	s_waitcnt lgkmcnt(0)
	ds_read_b64 v[102:103], v118 offset:248
	ds_read_b64 v[104:105], v118 offset:504
	ds_read_b64 v[106:107], v118 offset:760
	ds_read_b64 v[108:109], v118 offset:1016
	ds_read_b64 v[110:111], v118 offset:1272
	ds_read_b64 v[112:113], v118 offset:1528
	ds_read_b64 v[114:115], v118 offset:1784
	ds_read_b64 v[116:117], v118 offset:2040
	v_pk_fma_f32 v[70:71], v[86:87], v[62:63], v[70:71]
	v_pk_fma_f32 v[72:73], v[88:89], v[62:63], v[72:73]
	v_pk_fma_f32 v[74:75], v[90:91], v[62:63], v[74:75]
	v_pk_fma_f32 v[76:77], v[92:93], v[62:63], v[76:77]
	v_pk_fma_f32 v[78:79], v[94:95], v[62:63], v[78:79]
	v_pk_fma_f32 v[80:81], v[96:97], v[62:63], v[80:81]
	v_pk_fma_f32 v[82:83], v[98:99], v[62:63], v[82:83]
	v_pk_fma_f32 v[84:85], v[100:101], v[62:63], v[84:85]
	s_waitcnt lgkmcnt(0)
	v_pk_fma_f32 v[70:71], v[102:103], v[64:65], v[70:71]
	v_pk_fma_f32 v[72:73], v[104:105], v[64:65], v[72:73]
	v_pk_fma_f32 v[74:75], v[106:107], v[64:65], v[74:75]
	v_pk_fma_f32 v[76:77], v[108:109], v[64:65], v[76:77]
	v_pk_fma_f32 v[78:79], v[110:111], v[64:65], v[78:79]
	v_pk_fma_f32 v[80:81], v[112:113], v[64:65], v[80:81]
	v_pk_fma_f32 v[82:83], v[114:115], v[64:65], v[82:83]
	v_pk_fma_f32 v[84:85], v[116:117], v[64:65], v[84:85]
	s_waitcnt vmcnt(0)
	v_lshlrev_b32_e32 v180, 16, v180
	v_add_f32_e32 v70, v70, v71
	v_lshlrev_b32_e32 v181, 16, v181
	v_add_f32_e32 v72, v72, v73
	v_lshlrev_b32_e32 v182, 16, v182
	v_add_f32_e32 v74, v74, v75
	v_lshlrev_b32_e32 v183, 16, v183
	v_add_f32_e32 v76, v76, v77
	v_lshlrev_b32_e32 v184, 16, v184
	v_add_f32_e32 v78, v78, v79
	v_lshlrev_b32_e32 v185, 16, v185
	v_add_f32_e32 v80, v80, v81
	v_lshlrev_b32_e32 v186, 16, v186
	v_add_f32_e32 v82, v82, v83
	v_lshlrev_b32_e32 v187, 16, v187
	v_add_f32_e32 v84, v84, v85
	v_add_f32_e32 v70, v180, v70
	v_bfe_u32 v180, v70, 16, 1
	v_add_f32_e32 v72, v181, v72
	v_bfe_u32 v181, v72, 16, 1
	v_add_f32_e32 v74, v182, v74
	v_bfe_u32 v182, v74, 16, 1
	v_add_f32_e32 v76, v183, v76
	v_bfe_u32 v183, v76, 16, 1
	v_add_f32_e32 v78, v184, v78
	v_bfe_u32 v184, v78, 16, 1
	v_add_f32_e32 v80, v185, v80
	v_bfe_u32 v185, v80, 16, 1
	v_add_f32_e32 v82, v186, v82
	v_bfe_u32 v186, v82, 16, 1
	v_add_f32_e32 v84, v187, v84
	v_bfe_u32 v187, v84, 16, 1
	v_add3_u32 v70, v70, v180, s80
	v_add3_u32 v72, v72, v181, s80
	v_add3_u32 v74, v74, v182, s80
	v_add3_u32 v76, v76, v183, s80
	v_add3_u32 v78, v78, v184, s80
	v_add3_u32 v80, v80, v185, s80
	v_add3_u32 v82, v82, v186, s80
	v_add3_u32 v84, v84, v187, s80
	global_store_short_d16_hi v[122:123], v70, off offset:0
	global_store_short_d16_hi v[122:123], v72, off offset:2048
	v_lshl_add_u64 v[122:123], v[122:123], 0, s[12:13]
	global_store_short_d16_hi v[122:123], v74, off offset:0
	global_store_short_d16_hi v[122:123], v76, off offset:2048
	v_lshl_add_u64 v[122:123], v[122:123], 0, s[12:13]
	global_store_short_d16_hi v[122:123], v78, off offset:0
	global_store_short_d16_hi v[122:123], v80, off offset:2048
	v_lshl_add_u64 v[122:123], v[122:123], 0, s[12:13]
	global_store_short_d16_hi v[122:123], v82, off offset:0
	global_store_short_d16_hi v[122:123], v84, off offset:2048
	v_lshl_add_u64 v[122:123], v[122:123], 0, s[12:13]
	v_add_u32_e32 v118, 0x800, v118
	s_add_i32 s19, s19, 1
	s_cmp_lt_u32 s19, 8
	s_cbranch_scc1 .Lcorr_pass
	s_branch .LBB0_3056
